# nsa-sel-hoist-bias-reads
# speedup vs baseline: 1.0071x; 1.0007x over previous
; #define LAS __attribute__((address_space(3)))
; __device__ __forceinline__ float ex2(float x) { return __builtin_amdgcn_exp2f(x); }
; __device__ __forceinline__ float max3f(float a, float b, float c) { return __builtin_fmaxf(__builtin_fmaxf(a, b), c); }
;     __device__ __forceinline__ bool rowok(int t) const { return ((t < 32 ? (mlo >> t) : (mhi >> (t - 32))) & 1u) != 0u; }
;     __device__ __forceinline__ bool rowok(int t, int sub) const { const unsigned lo = sub ? mloB : mloA, hh = sub ? mhiB : mhiA; return ((t < 32 ? (lo >> t) : (hh >> (t - 32))) & 1u) != 0u; }
; __device__ __forceinline__ void softmax_step(v16f& p0, v16f& p1, v16f (&oT)[2], float& m, float& l, bool rowok) {
;     float a = max3f(p0[0], p0[1], p1[0]), b = max3f(p0[2], p0[3], p1[1]); a = max3f(a, p1[2], p1[3]);
; #pragma unroll
;     for (int r = 4; r < 16; r += 4) { a = max3f(a, p0[r], p0[r + 1]); b = max3f(b, p0[r + 2], p0[r + 3]); a = max3f(a, p1[r], p1[r + 1]); b = max3f(b, p1[r + 2], p1[r + 3]); }
;     float mx = fmaxf(a, b);
;     mx = xhalf_max(mx);
;     if (!rowok) mx = -INFINITY;
;     float mn = m;
;     if (__any(mx > m + SM_THR)) {
;         mn = fmaxf(m, mx);
;         const float mu_ = (mn == -INFINITY) ? 0.f : mn;
;         const float alpha = ex2(m - mu_);
;         oT[0] = oT[0] * alpha; oT[1] = oT[1] * alpha; l *= alpha;
;     }
;     __device__ __forceinline__ void apply_tab(v16f& p0, v16f& p1, int t) const {
;         const LAS float* bp = tb + (NEGPAD + qpos - 64 * t - 63 - 4 * hi);
;         v16f c0, c1;
; #pragma unroll
;         for (int r = 0; r < 16; ++r) { c0[r] = bp[63 - ((r & 3) + 8 * (r >> 2))]; c1[r] = bp[31 - ((r & 3) + 8 * (r >> 2))]; }
.LBB0_535:
	s_mul_i32 s0, s54, 0x2080
	v_add_u32_e32 v0, s0, v201
	ds_read_b64_tr_b16 v[174:175], v0 offset:28672
	ds_read_b64_tr_b16 v[176:177], v0 offset:29184
	ds_read_b64_tr_b16 v[166:167], v0 offset:29696
	ds_read_b64_tr_b16 v[168:169], v0 offset:30208
	ds_read_b64_tr_b16 v[170:171], v0 offset:32832
	ds_read_b64_tr_b16 v[172:173], v0 offset:33344
	ds_read_b64_tr_b16 v[162:163], v0 offset:33856
	ds_read_b64_tr_b16 v[164:165], v0 offset:34368
	ds_read_b64_tr_b16 v[178:179], v0 offset:31808
	ds_read_b64_tr_b16 v[180:181], v0 offset:32320
	ds_read_b64_tr_b16 v[158:159], v0 offset:30720
	ds_read_b64_tr_b16 v[160:161], v0 offset:31232
	ds_read_b64_tr_b16 v[182:183], v0 offset:27648
	ds_read_b64_tr_b16 v[184:185], v0 offset:28160
	ds_read_b64_tr_b16 v[154:155], v0 offset:34880
	ds_read_b64_tr_b16 v[156:157], v0 offset:35392
	v_lshl_add_u32 v237, s50, 6, v200
	v_sub_u32_e32 v237, v199, v237
	v_lshl_add_u32 v237, v237, 2, s37
	v_add_u32_e32 v237, 0xd110, v237
	ds_read2_b32 v[218:219], v237 offset0:58 offset1:59
	ds_read2_b32 v[220:221], v237 offset0:26 offset1:27
	ds_read2_b32 v[222:223], v237 offset0:56 offset1:57
	ds_read2_b32 v[224:225], v237 offset0:24 offset1:25
	ds_read2_b32 v[226:227], v237 offset0:50 offset1:51
	ds_read2_b32 v[228:229], v237 offset0:18 offset1:19
	ds_read2_b32 v[230:231], v237 offset0:48 offset1:49
	ds_read2_b32 v[232:233], v237 offset0:16 offset1:17
	ds_read2_b32 v[244:245], v237 offset0:42 offset1:43
	ds_read2_b32 v[246:247], v237 offset0:10 offset1:11
	ds_read2_b32 v[248:249], v237 offset0:40 offset1:41
	ds_read2_b32 v[250:251], v237 offset0:8 offset1:9
	ds_read2_b32 v[252:253], v237 offset0:34 offset1:35
	ds_read2_b32 v[208:209], v237 offset0:32 offset1:33
	ds_read2_b32 v[210:211], v237 offset0:0 offset1:1
	ds_read2_b32 v[212:213], v237 offset0:2 offset1:3
	v_sub_co_u32_e64 v0, vcc, s56, 32
	v_lshrrev_b32_e32 v204, s56, v188
	v_lshrrev_b32_e32 v0, v0, v189
	v_cndmask_b32_e32 v0, v0, v204, vcc
	v_and_b32_e32 v0, 1, v0
	v_cmp_eq_u32_e64 s[0:1], 0, v0
	v_max_f32_e32 v0, v67, v67
	v_max_f32_e32 v204, v66, v66
	v_max_f32_e32 v0, v204, v0
	v_max3_f32 v204, v68, v69, v83
	v_max3_f32 v0, v0, v82, v84
	v_max3_f32 v0, v0, v85, v70
	v_max3_f32 v204, v204, v72, v73
	v_max3_f32 v0, v0, v71, v86
	v_max3_f32 v204, v204, v88, v89
	v_max3_f32 v0, v0, v87, v74
	v_max3_f32 v204, v204, v76, v77
	v_max3_f32 v0, v0, v75, v90
	v_max3_f32 v204, v204, v92, v93
	v_max3_f32 v0, v0, v91, v78
	v_max3_f32 v204, v204, v80, v81
	v_max3_f32 v0, v0, v79, v94
	v_max3_f32 v204, v204, v96, v97
	v_max3_f32 v0, v0, v95, v204
	v_mov_b32_e32 v204, v0
	s_nop 1
	v_permlane32_swap_b32_e32 v0, v204
	v_max_f32_e32 v204, v204, v204
	v_max_f32_e32 v0, v0, v0
	v_max_f32_e32 v0, v0, v204
	v_cndmask_b32_e64 v0, v0, v241, s[0:1]
	v_add_f32_e32 v204, 0x41800000, v217
	v_cmp_gt_f32_e32 vcc, v0, v204
	s_cbranch_vccz .LBB0_537
	v_max_f32_e32 v0, v0, v0
	v_max_f32_e32 v2, v217, v217
	v_max_f32_e32 v204, v2, v0
	v_cmp_neq_f32_e32 vcc, s76, v204
	s_nop 1
	v_cndmask_b32_e32 v0, 0, v204, vcc
	v_sub_f32_e32 v0, v217, v0
	v_exp_f32_e32 v0, v0
	v_mov_b32_e32 v217, v204
	v_pk_mul_f32 v[64:65], v[64:65], v[0:1] op_sel_hi:[1,0]
	v_pk_mul_f32 v[62:63], v[62:63], v[0:1] op_sel_hi:[1,0]
	v_pk_mul_f32 v[60:61], v[60:61], v[0:1] op_sel_hi:[1,0]
	v_pk_mul_f32 v[58:59], v[58:59], v[0:1] op_sel_hi:[1,0]
	v_pk_mul_f32 v[56:57], v[56:57], v[0:1] op_sel_hi:[1,0]
	v_pk_mul_f32 v[54:55], v[54:55], v[0:1] op_sel_hi:[1,0]
	v_pk_mul_f32 v[52:53], v[52:53], v[0:1] op_sel_hi:[1,0]
	v_pk_mul_f32 v[50:51], v[50:51], v[0:1] op_sel_hi:[1,0]
	v_pk_mul_f32 v[48:49], v[48:49], v[0:1] op_sel_hi:[1,0]
	v_pk_mul_f32 v[46:47], v[46:47], v[0:1] op_sel_hi:[1,0]
	v_pk_mul_f32 v[44:45], v[44:45], v[0:1] op_sel_hi:[1,0]
	v_pk_mul_f32 v[42:43], v[42:43], v[0:1] op_sel_hi:[1,0]
	v_pk_mul_f32 v[40:41], v[40:41], v[0:1] op_sel_hi:[1,0]
	v_pk_mul_f32 v[38:39], v[38:39], v[0:1] op_sel_hi:[1,0]
	v_pk_mul_f32 v[36:37], v[36:37], v[0:1] op_sel_hi:[1,0]
	v_pk_mul_f32 v[34:35], v[34:35], v[0:1] op_sel_hi:[1,0]
	v_mul_f32_e32 v216, v216, v0
; #define LAS __attribute__((address_space(3)))
; __device__ __forceinline__ v16f mfma32(v8s a, v8s b, v16f c) { return __builtin_amdgcn_mfma_f32_32x32x16_bf16(a, b, c, 0, 0, 0); }
; __device__ __forceinline__ void pv_mma(const v4s (&vf)[16], const v16f& p0, const v16f& p1, v16f (&oT)[2]) {
;     v4u w[4];
;     w[0] = (v4u){pkbf(p0[0], p0[1]), pkbf(p0[2], p0[3]), pkbf(p0[4], p0[5]), pkbf(p0[6], p0[7])};
;     w[1] = (v4u){pkbf(p0[8], p0[9]), pkbf(p0[10], p0[11]), pkbf(p0[12], p0[13]), pkbf(p0[14], p0[15])};
;     w[2] = (v4u){pkbf(p1[0], p1[1]), pkbf(p1[2], p1[3]), pkbf(p1[4], p1[5]), pkbf(p1[6], p1[7])};
;     w[3] = (v4u){pkbf(p1[8], p1[9]), pkbf(p1[10], p1[11]), pkbf(p1[12], p1[13]), pkbf(p1[14], p1[15])};
; #pragma unroll
;     for (int ks = 0; ks < 4; ++ks)
; #pragma unroll
;         for (int dt = 0; dt < 2; ++dt) {
;             const v4s lo = vf[4 * ks + 2 * dt], h4 = vf[4 * ks + 2 * dt + 1];
;             const v8s af = (v8s){lo[0], lo[1], lo[2], lo[3], h4[0], h4[1], h4[2], h4[3]};
;             oT[dt] = mfma32(af, __builtin_bit_cast(v8s, w[ks]), oT[dt]);
;         }
;     __device__ __forceinline__ void apply_tab(v16f& p0, v16f& p1, int t) const {
;         const LAS float* bp = tb + (NEGPAD + qpos - 64 * t - 63 - 4 * hi);
;         v16f c0, c1;
; #pragma unroll
;         for (int r = 0; r < 16; ++r) { c0[r] = bp[63 - ((r & 3) + 8 * (r >> 2))]; c1[r] = bp[31 - ((r & 3) + 8 * (r >> 2))]; }
;         p0 = p0 * C1 + c0; p1 = p1 * C1 + c1;
;     }
.LBB0_537:
	v_cmp_neq_f32_e32 vcc, s76, v217
	s_nop 1
	v_cndmask_b32_e32 v0, 0, v217, vcc
	v_cndmask_b32_e64 v6, v0, v240, s[0:1]
	v_sub_f32_e32 v2, v73, v6
	v_sub_f32_e32 v3, v72, v6
	v_sub_f32_e32 v4, v71, v6
	v_sub_f32_e32 v5, v70, v6
	v_sub_f32_e32 v15, v69, v6
	v_sub_f32_e32 v16, v68, v6
	v_sub_f32_e32 v17, v67, v6
	v_sub_f32_e32 v18, v66, v6
	v_exp_f32_e32 v66, v18
	v_exp_f32_e32 v67, v17
	v_exp_f32_e32 v68, v16
	v_exp_f32_e32 v69, v15
	v_exp_f32_e32 v70, v5
	v_exp_f32_e32 v71, v4
	v_exp_f32_e32 v72, v3
	v_exp_f32_e32 v73, v2
	v_cvt_pk_bf16_f32 v2, v66, v67
	v_cvt_pk_bf16_f32 v3, v68, v69
	v_cvt_pk_bf16_f32 v4, v70, v71
	v_cvt_pk_bf16_f32 v5, v72, v73
	v_sub_f32_e32 v7, v81, v6
	v_sub_f32_e32 v8, v80, v6
	s_waitcnt lgkmcnt(2)
	v_mfma_f32_32x32x16_bf16 v[34:49], v[182:185], v[2:5], v[34:49]
	v_sub_f32_e32 v9, v79, v6
	v_sub_f32_e32 v10, v78, v6
	v_sub_f32_e32 v11, v77, v6
	v_sub_f32_e32 v12, v76, v6
	v_sub_f32_e32 v13, v75, v6
	v_sub_f32_e32 v14, v74, v6
	v_exp_f32_e32 v74, v14
	v_mfma_f32_32x32x16_bf16 v[50:65], v[178:181], v[2:5], v[50:65]
	v_exp_f32_e32 v75, v13
	v_exp_f32_e32 v76, v12
	v_exp_f32_e32 v77, v11
	v_exp_f32_e32 v78, v10
	v_exp_f32_e32 v79, v9
	v_exp_f32_e32 v80, v8
	v_exp_f32_e32 v81, v7
	v_cvt_pk_bf16_f32 v2, v74, v75
	v_cvt_pk_bf16_f32 v3, v76, v77
	v_cvt_pk_bf16_f32 v4, v78, v79
	v_cvt_pk_bf16_f32 v5, v80, v81
	v_sub_f32_e32 v26, v89, v6
	v_sub_f32_e32 v27, v88, v6
	v_mfma_f32_32x32x16_bf16 v[34:49], v[174:177], v[2:5], v[34:49]
	v_sub_f32_e32 v28, v87, v6
	v_sub_f32_e32 v29, v86, v6
	v_sub_f32_e32 v15, v85, v6
	v_sub_f32_e32 v16, v84, v6
	v_sub_f32_e32 v7, v83, v6
	v_sub_f32_e32 v8, v82, v6
	v_exp_f32_e32 v82, v8
	v_mfma_f32_32x32x16_bf16 v[50:65], v[170:173], v[2:5], v[50:65]
	v_exp_f32_e32 v83, v7
	v_exp_f32_e32 v84, v16
	v_exp_f32_e32 v85, v15
	v_exp_f32_e32 v86, v29
	v_exp_f32_e32 v87, v28
	v_exp_f32_e32 v88, v27
	v_exp_f32_e32 v89, v26
	v_cvt_pk_bf16_f32 v2, v82, v83
	v_cvt_pk_bf16_f32 v3, v84, v85
	v_cvt_pk_bf16_f32 v4, v86, v87
	v_cvt_pk_bf16_f32 v5, v88, v89
	v_sub_f32_e32 v19, v97, v6
	v_sub_f32_e32 v20, v96, v6
	v_mfma_f32_32x32x16_bf16 v[34:49], v[166:169], v[2:5], v[34:49]
	v_sub_f32_e32 v21, v95, v6
	v_sub_f32_e32 v22, v94, v6
	v_sub_f32_e32 v23, v93, v6
	v_sub_f32_e32 v24, v92, v6
	v_sub_f32_e32 v25, v91, v6
	v_sub_f32_e32 v6, v90, v6
	v_exp_f32_e32 v90, v6
	v_mfma_f32_32x32x16_bf16 v[50:65], v[162:165], v[2:5], v[50:65]
	v_exp_f32_e32 v91, v25
	v_exp_f32_e32 v92, v24
	v_exp_f32_e32 v93, v23
	v_exp_f32_e32 v94, v22
	v_exp_f32_e32 v95, v21
	v_exp_f32_e32 v96, v20
	v_exp_f32_e32 v97, v19
	s_nop 3
	v_cvt_pk_bf16_f32 v162, v90, v91
	v_cvt_pk_bf16_f32 v163, v92, v93
	v_cvt_pk_bf16_f32 v164, v94, v95
	v_cvt_pk_bf16_f32 v165, v96, v97
	s_nop 1
	v_mfma_f32_32x32x16_bf16 v[34:49], v[158:161], v[162:165], v[34:49]
	s_andn2_b64 vcc, exec, s[24:25]
	s_waitcnt lgkmcnt(0)
	v_mfma_f32_32x32x16_bf16 v[50:65], v[154:157], v[162:165], v[50:65]
	s_cbranch_vccnz .LBB0_543
	s_lshl_b32 s24, s50, 6
	s_sub_i32 s0, s49, s24
	s_cmpk_lt_i32 s0, 0x400
	s_mov_b64 s[0:1], -1
	s_cbranch_scc0 .LBB0_540
	s_waitcnt lgkmcnt(0)
	v_pk_fma_f32 v[114:115], v[114:115], s[52:53], v[218:219] op_sel:[0,0,1] op_sel_hi:[1,0,0]
	v_pk_fma_f32 v[98:99], v[98:99], s[52:53], v[220:221] op_sel:[0,0,1] op_sel_hi:[1,0,0]
	v_pk_fma_f32 v[116:117], v[116:117], s[52:53], v[222:223] op_sel:[0,0,1] op_sel_hi:[1,0,0]
	v_pk_fma_f32 v[100:101], v[100:101], s[52:53], v[224:225] op_sel:[0,0,1] op_sel_hi:[1,0,0]
	v_pk_fma_f32 v[118:119], v[118:119], s[52:53], v[226:227] op_sel:[0,0,1] op_sel_hi:[1,0,0]
	v_pk_fma_f32 v[102:103], v[102:103], s[52:53], v[228:229] op_sel:[0,0,1] op_sel_hi:[1,0,0]
	v_pk_fma_f32 v[120:121], v[120:121], s[52:53], v[230:231] op_sel:[0,0,1] op_sel_hi:[1,0,0]
	v_pk_fma_f32 v[104:105], v[104:105], s[52:53], v[232:233] op_sel:[0,0,1] op_sel_hi:[1,0,0]
	v_pk_fma_f32 v[122:123], v[122:123], s[52:53], v[244:245] op_sel:[0,0,1] op_sel_hi:[1,0,0]
	v_pk_fma_f32 v[106:107], v[106:107], s[52:53], v[246:247] op_sel:[0,0,1] op_sel_hi:[1,0,0]
	v_pk_fma_f32 v[124:125], v[124:125], s[52:53], v[248:249] op_sel:[0,0,1] op_sel_hi:[1,0,0]
	v_pk_fma_f32 v[108:109], v[108:109], s[52:53], v[250:251] op_sel:[0,0,1] op_sel_hi:[1,0,0]
	v_pk_fma_f32 v[126:127], v[126:127], s[52:53], v[252:253] op_sel:[0,0,1] op_sel_hi:[1,0,0]
	v_pk_fma_f32 v[128:129], v[128:129], s[52:53], v[208:209] op_sel:[0,0,1] op_sel_hi:[1,0,0]
	v_pk_fma_f32 v[112:113], v[112:113], s[52:53], v[210:211] op_sel:[0,0,1] op_sel_hi:[1,0,0]
	v_pk_fma_f32 v[110:111], v[110:111], s[52:53], v[212:213] op_sel:[0,0,1] op_sel_hi:[1,0,0]
	s_mov_b64 s[0:1], 0
	s_branch .LBB0_543

; #define LAS __attribute__((address_space(3)))
; __device__ __forceinline__ float ex2(float x) { return __builtin_amdgcn_exp2f(x); }
; __device__ __forceinline__ float max3f(float a, float b, float c) { return __builtin_fmaxf(__builtin_fmaxf(a, b), c); }
;     __device__ __forceinline__ bool rowok(int t) const { return ((t < 32 ? (mlo >> t) : (mhi >> (t - 32))) & 1u) != 0u; }
;     __device__ __forceinline__ bool rowok(int t, int sub) const { const unsigned lo = sub ? mloB : mloA, hh = sub ? mhiB : mhiA; return ((t < 32 ? (lo >> t) : (hh >> (t - 32))) & 1u) != 0u; }
; __device__ __forceinline__ void softmax_step(v16f& p0, v16f& p1, v16f (&oT)[2], float& m, float& l, bool rowok) {
;     float a = max3f(p0[0], p0[1], p1[0]), b = max3f(p0[2], p0[3], p1[1]); a = max3f(a, p1[2], p1[3]);
; #pragma unroll
;     for (int r = 4; r < 16; r += 4) { a = max3f(a, p0[r], p0[r + 1]); b = max3f(b, p0[r + 2], p0[r + 3]); a = max3f(a, p1[r], p1[r + 1]); b = max3f(b, p1[r + 2], p1[r + 3]); }
;     float mx = fmaxf(a, b);
;     mx = xhalf_max(mx);
;     if (!rowok) mx = -INFINITY;
;     float mn = m;
;     if (__any(mx > m + SM_THR)) {
;         mn = fmaxf(m, mx);
;         const float mu_ = (mn == -INFINITY) ? 0.f : mn;
;         const float alpha = ex2(m - mu_);
;         oT[0] = oT[0] * alpha; oT[1] = oT[1] * alpha; l *= alpha;
;     }
;     __device__ __forceinline__ void apply_tab(v16f& p0, v16f& p1, int t) const {
;         const LAS float* bp = tb + (NEGPAD + qpos - 64 * t - 63 - 4 * hi);
;         v16f c0, c1;
; #pragma unroll
;         for (int r = 0; r < 16; ++r) { c0[r] = bp[63 - ((r & 3) + 8 * (r >> 2))]; c1[r] = bp[31 - ((r & 3) + 8 * (r >> 2))]; }
.LBB0_550:
	s_mulk_i32 s55, 0x2080
	v_add_u32_e32 v4, s55, v201
	ds_read_b64_tr_b16 v[22:23], v4 offset:28672
	ds_read_b64_tr_b16 v[24:25], v4 offset:29184
	ds_read_b64_tr_b16 v[14:15], v4 offset:29696
	ds_read_b64_tr_b16 v[16:17], v4 offset:30208
	ds_read_b64_tr_b16 v[18:19], v4 offset:32832
	ds_read_b64_tr_b16 v[20:21], v4 offset:33344
	ds_read_b64_tr_b16 v[10:11], v4 offset:33856
	ds_read_b64_tr_b16 v[12:13], v4 offset:34368
	ds_read_b64_tr_b16 v[26:27], v4 offset:31808
	ds_read_b64_tr_b16 v[28:29], v4 offset:32320
	ds_read_b64_tr_b16 v[6:7], v4 offset:30720
	ds_read_b64_tr_b16 v[8:9], v4 offset:31232
	ds_read_b64_tr_b16 v[30:31], v4 offset:27648
	ds_read_b64_tr_b16 v[32:33], v4 offset:28160
	ds_read_b64_tr_b16 v[2:3], v4 offset:34880
	ds_read_b64_tr_b16 v[4:5], v4 offset:35392
	v_lshl_add_u32 v237, s26, 6, v200
	v_sub_u32_e32 v237, v199, v237
	v_lshl_add_u32 v237, v237, 2, s37
	v_add_u32_e32 v237, 0xd110, v237
	ds_read2_b32 v[218:219], v237 offset0:58 offset1:59
	ds_read2_b32 v[220:221], v237 offset0:26 offset1:27
	ds_read2_b32 v[222:223], v237 offset0:56 offset1:57
	ds_read2_b32 v[224:225], v237 offset0:24 offset1:25
	ds_read2_b32 v[226:227], v237 offset0:50 offset1:51
	ds_read2_b32 v[228:229], v237 offset0:18 offset1:19
	ds_read2_b32 v[230:231], v237 offset0:48 offset1:49
	ds_read2_b32 v[232:233], v237 offset0:16 offset1:17
	ds_read2_b32 v[244:245], v237 offset0:42 offset1:43
	ds_read2_b32 v[246:247], v237 offset0:10 offset1:11
	ds_read2_b32 v[248:249], v237 offset0:40 offset1:41
	ds_read2_b32 v[250:251], v237 offset0:8 offset1:9
	ds_read2_b32 v[252:253], v237 offset0:34 offset1:35
	ds_read2_b32 v[208:209], v237 offset0:32 offset1:33
	ds_read2_b32 v[210:211], v237 offset0:0 offset1:1
	ds_read2_b32 v[212:213], v237 offset0:2 offset1:3
	v_sub_co_u32_e64 v154, vcc, s50, 32
	v_lshrrev_b32_e32 v155, s50, v188
	v_lshrrev_b32_e32 v154, v154, v189
	v_cndmask_b32_e32 v154, v154, v155, vcc
	v_and_b32_e32 v154, 1, v154
	v_cmp_eq_u32_e64 s[4:5], 0, v154
	v_max_f32_e32 v154, v115, v115
	v_max_f32_e32 v155, v114, v114
	v_max_f32_e32 v154, v155, v154
	v_max3_f32 v155, v116, v117, v99
	v_max3_f32 v154, v154, v98, v100
	v_max3_f32 v154, v154, v101, v118
	v_max3_f32 v155, v155, v120, v121
	v_max3_f32 v154, v154, v119, v102
	v_max3_f32 v155, v155, v104, v105
	v_max3_f32 v154, v154, v103, v122
	v_max3_f32 v155, v155, v124, v125
	v_max3_f32 v154, v154, v123, v106
	v_max3_f32 v155, v155, v108, v109
	v_max3_f32 v154, v154, v107, v126
	v_max3_f32 v155, v155, v128, v129
	v_max3_f32 v154, v154, v127, v110
	v_max3_f32 v155, v155, v112, v113
	v_max3_f32 v154, v154, v111, v155
	v_mov_b32_e32 v155, v154
	s_nop 1
	v_permlane32_swap_b32_e32 v154, v155
	v_max_f32_e32 v155, v155, v155
	v_max_f32_e32 v154, v154, v154
	v_max_f32_e32 v154, v154, v155
	v_cndmask_b32_e64 v154, v154, v241, s[4:5]
	v_add_f32_e32 v155, 0x41800000, v217
	v_cmp_gt_f32_e32 vcc, v154, v155
	s_cbranch_vccz .LBB0_552
	v_max_f32_e32 v0, v154, v154
	v_max_f32_e32 v154, v217, v217
	v_max_f32_e32 v155, v154, v0
	v_cmp_neq_f32_e32 vcc, s76, v155
	s_nop 1
	v_cndmask_b32_e32 v0, 0, v155, vcc
	v_sub_f32_e32 v154, v217, v0
	v_exp_f32_e32 v154, v154
	v_mov_b32_e32 v217, v155
	v_pk_mul_f32 v[48:49], v[48:49], v[154:155] op_sel_hi:[1,0]
	v_pk_mul_f32 v[46:47], v[46:47], v[154:155] op_sel_hi:[1,0]
	v_pk_mul_f32 v[44:45], v[44:45], v[154:155] op_sel_hi:[1,0]
	v_pk_mul_f32 v[42:43], v[42:43], v[154:155] op_sel_hi:[1,0]
	v_pk_mul_f32 v[40:41], v[40:41], v[154:155] op_sel_hi:[1,0]
	v_pk_mul_f32 v[38:39], v[38:39], v[154:155] op_sel_hi:[1,0]
	v_pk_mul_f32 v[36:37], v[36:37], v[154:155] op_sel_hi:[1,0]
	v_pk_mul_f32 v[34:35], v[34:35], v[154:155] op_sel_hi:[1,0]
	v_pk_mul_f32 v[64:65], v[64:65], v[154:155] op_sel_hi:[1,0]
	v_pk_mul_f32 v[62:63], v[62:63], v[154:155] op_sel_hi:[1,0]
	v_pk_mul_f32 v[60:61], v[60:61], v[154:155] op_sel_hi:[1,0]
	v_pk_mul_f32 v[58:59], v[58:59], v[154:155] op_sel_hi:[1,0]
	v_pk_mul_f32 v[56:57], v[56:57], v[154:155] op_sel_hi:[1,0]
	v_pk_mul_f32 v[54:55], v[54:55], v[154:155] op_sel_hi:[1,0]
	v_pk_mul_f32 v[52:53], v[52:53], v[154:155] op_sel_hi:[1,0]
	v_pk_mul_f32 v[50:51], v[50:51], v[154:155] op_sel_hi:[1,0]
	v_mul_f32_e32 v216, v216, v154
; #define LAS __attribute__((address_space(3)))
; __device__ __forceinline__ v16f mfma32(v8s a, v8s b, v16f c) { return __builtin_amdgcn_mfma_f32_32x32x16_bf16(a, b, c, 0, 0, 0); }
; __device__ __forceinline__ void pv_mma(const v4s (&vf)[16], const v16f& p0, const v16f& p1, v16f (&oT)[2]) {
;     v4u w[4];
;     w[0] = (v4u){pkbf(p0[0], p0[1]), pkbf(p0[2], p0[3]), pkbf(p0[4], p0[5]), pkbf(p0[6], p0[7])};
;     w[1] = (v4u){pkbf(p0[8], p0[9]), pkbf(p0[10], p0[11]), pkbf(p0[12], p0[13]), pkbf(p0[14], p0[15])};
;     w[2] = (v4u){pkbf(p1[0], p1[1]), pkbf(p1[2], p1[3]), pkbf(p1[4], p1[5]), pkbf(p1[6], p1[7])};
;     w[3] = (v4u){pkbf(p1[8], p1[9]), pkbf(p1[10], p1[11]), pkbf(p1[12], p1[13]), pkbf(p1[14], p1[15])};
; #pragma unroll
;     for (int ks = 0; ks < 4; ++ks)
; #pragma unroll
;         for (int dt = 0; dt < 2; ++dt) {
;             const v4s lo = vf[4 * ks + 2 * dt], h4 = vf[4 * ks + 2 * dt + 1];
;             const v8s af = (v8s){lo[0], lo[1], lo[2], lo[3], h4[0], h4[1], h4[2], h4[3]};
;             oT[dt] = mfma32(af, __builtin_bit_cast(v8s, w[ks]), oT[dt]);
;         }
;     __device__ __forceinline__ void apply_tab(v16f& p0, v16f& p1, int t) const {
;         const LAS float* bp = tb + (NEGPAD + qpos - 64 * t - 63 - 4 * hi);
;         v16f c0, c1;
; #pragma unroll
;         for (int r = 0; r < 16; ++r) { c0[r] = bp[63 - ((r & 3) + 8 * (r >> 2))]; c1[r] = bp[31 - ((r & 3) + 8 * (r >> 2))]; }
;         p0 = p0 * C1 + c0; p1 = p1 * C1 + c1;
;     }
.LBB0_552:
	v_cndmask_b32_e64 v0, v0, v240, s[4:5]
	v_sub_f32_e32 v121, v121, v0
	v_sub_f32_e32 v120, v120, v0
	v_sub_f32_e32 v119, v119, v0
	v_sub_f32_e32 v118, v118, v0
	v_sub_f32_e32 v117, v117, v0
	v_sub_f32_e32 v116, v116, v0
	v_sub_f32_e32 v115, v115, v0
	v_sub_f32_e32 v114, v114, v0
	v_exp_f32_e32 v114, v114
	v_exp_f32_e32 v115, v115
	v_exp_f32_e32 v116, v116
	v_exp_f32_e32 v117, v117
	v_exp_f32_e32 v118, v118
	v_exp_f32_e32 v119, v119
	v_exp_f32_e32 v120, v120
	v_exp_f32_e32 v121, v121
	v_sub_f32_e32 v154, v105, v0
	v_sub_f32_e32 v155, v104, v0
	v_sub_f32_e32 v156, v103, v0
	v_sub_f32_e32 v157, v102, v0
	v_cvt_pk_bf16_f32 v102, v114, v115
	v_cvt_pk_bf16_f32 v103, v116, v117
	v_cvt_pk_bf16_f32 v104, v118, v119
	v_cvt_pk_bf16_f32 v105, v120, v121
	v_sub_f32_e32 v129, v129, v0
	v_sub_f32_e32 v128, v128, v0
	s_waitcnt lgkmcnt(2)
	v_mfma_f32_32x32x16_bf16 v[34:49], v[30:33], v[102:105], v[34:49]
	v_sub_f32_e32 v127, v127, v0
	v_sub_f32_e32 v126, v126, v0
	v_sub_f32_e32 v125, v125, v0
	v_sub_f32_e32 v124, v124, v0
	v_sub_f32_e32 v123, v123, v0
	v_sub_f32_e32 v122, v122, v0
	v_exp_f32_e32 v122, v122
	v_mfma_f32_32x32x16_bf16 v[50:65], v[26:29], v[102:105], v[50:65]
	v_exp_f32_e32 v123, v123
	v_exp_f32_e32 v124, v124
	v_exp_f32_e32 v125, v125
	v_exp_f32_e32 v126, v126
	v_exp_f32_e32 v127, v127
	v_exp_f32_e32 v128, v128
	v_exp_f32_e32 v129, v129
	v_cvt_pk_bf16_f32 v26, v122, v123
	v_cvt_pk_bf16_f32 v27, v124, v125
	v_cvt_pk_bf16_f32 v28, v126, v127
	v_cvt_pk_bf16_f32 v29, v128, v129
	v_sub_f32_e32 v30, v101, v0
	v_sub_f32_e32 v31, v100, v0
	v_mfma_f32_32x32x16_bf16 v[34:49], v[22:25], v[26:29], v[34:49]
	v_sub_f32_e32 v22, v99, v0
	v_sub_f32_e32 v23, v98, v0
	v_exp_f32_e32 v98, v23
	v_exp_f32_e32 v99, v22
	v_exp_f32_e32 v100, v31
	v_exp_f32_e32 v101, v30
	v_exp_f32_e32 v102, v157
	v_mfma_f32_32x32x16_bf16 v[50:65], v[18:21], v[26:29], v[50:65]
	v_exp_f32_e32 v103, v156
	v_exp_f32_e32 v104, v155
	v_exp_f32_e32 v105, v154
	v_cvt_pk_bf16_f32 v18, v98, v99
	v_cvt_pk_bf16_f32 v19, v100, v101
	v_cvt_pk_bf16_f32 v20, v102, v103
	v_cvt_pk_bf16_f32 v21, v104, v105
	v_sub_f32_e32 v113, v113, v0
	v_sub_f32_e32 v112, v112, v0
	v_mfma_f32_32x32x16_bf16 v[34:49], v[14:17], v[18:21], v[34:49]
	v_sub_f32_e32 v111, v111, v0
	v_sub_f32_e32 v110, v110, v0
	v_sub_f32_e32 v109, v109, v0
	v_sub_f32_e32 v108, v108, v0
	v_sub_f32_e32 v14, v107, v0
	v_sub_f32_e32 v0, v106, v0
	v_exp_f32_e32 v106, v0
	v_mfma_f32_32x32x16_bf16 v[50:65], v[10:13], v[18:21], v[50:65]
	v_exp_f32_e32 v107, v14
	v_exp_f32_e32 v108, v108
	v_exp_f32_e32 v109, v109
	v_exp_f32_e32 v110, v110
	v_exp_f32_e32 v111, v111
	v_exp_f32_e32 v112, v112
	v_exp_f32_e32 v113, v113
	v_cvt_pk_bf16_f32 v10, v106, v107
	v_cvt_pk_bf16_f32 v11, v108, v109
	v_cvt_pk_bf16_f32 v12, v110, v111
	v_cvt_pk_bf16_f32 v13, v112, v113
	s_and_b64 vcc, exec, s[0:1]
	s_nop 0
	v_mfma_f32_32x32x16_bf16 v[34:49], v[6:9], v[10:13], v[34:49]
	s_waitcnt lgkmcnt(0)
	v_mfma_f32_32x32x16_bf16 v[50:65], v[2:5], v[10:13], v[50:65]
	s_cbranch_vccnz .LBB0_558
	s_lshl_b32 s4, s26, 6
	s_sub_i32 s0, s49, s4
	s_cmpk_lt_i32 s0, 0x400
	s_mov_b64 s[0:1], -1
	s_cbranch_scc0 .LBB0_555
	s_waitcnt lgkmcnt(0)
	v_pk_fma_f32 v[66:67], v[66:67], s[52:53], v[218:219] op_sel:[0,0,1] op_sel_hi:[1,0,0]
	v_pk_fma_f32 v[82:83], v[82:83], s[52:53], v[220:221] op_sel:[0,0,1] op_sel_hi:[1,0,0]
	v_pk_fma_f32 v[68:69], v[68:69], s[52:53], v[222:223] op_sel:[0,0,1] op_sel_hi:[1,0,0]
	v_pk_fma_f32 v[84:85], v[84:85], s[52:53], v[224:225] op_sel:[0,0,1] op_sel_hi:[1,0,0]
	v_pk_fma_f32 v[70:71], v[70:71], s[52:53], v[226:227] op_sel:[0,0,1] op_sel_hi:[1,0,0]
	v_pk_fma_f32 v[86:87], v[86:87], s[52:53], v[228:229] op_sel:[0,0,1] op_sel_hi:[1,0,0]
	v_pk_fma_f32 v[72:73], v[72:73], s[52:53], v[230:231] op_sel:[0,0,1] op_sel_hi:[1,0,0]
	v_pk_fma_f32 v[88:89], v[88:89], s[52:53], v[232:233] op_sel:[0,0,1] op_sel_hi:[1,0,0]
	v_pk_fma_f32 v[74:75], v[74:75], s[52:53], v[244:245] op_sel:[0,0,1] op_sel_hi:[1,0,0]
	v_pk_fma_f32 v[90:91], v[90:91], s[52:53], v[246:247] op_sel:[0,0,1] op_sel_hi:[1,0,0]
	v_pk_fma_f32 v[76:77], v[76:77], s[52:53], v[248:249] op_sel:[0,0,1] op_sel_hi:[1,0,0]
	v_pk_fma_f32 v[92:93], v[92:93], s[52:53], v[250:251] op_sel:[0,0,1] op_sel_hi:[1,0,0]
	v_pk_fma_f32 v[78:79], v[78:79], s[52:53], v[252:253] op_sel:[0,0,1] op_sel_hi:[1,0,0]
	v_pk_fma_f32 v[80:81], v[80:81], s[52:53], v[208:209] op_sel:[0,0,1] op_sel_hi:[1,0,0]
	v_pk_fma_f32 v[96:97], v[96:97], s[52:53], v[210:211] op_sel:[0,0,1] op_sel_hi:[1,0,0]
	v_pk_fma_f32 v[94:95], v[94:95], s[52:53], v[212:213] op_sel:[0,0,1] op_sel_hi:[1,0,0]
	s_mov_b64 s[0:1], 0
	s_branch .LBB0_558
